# speedup vs baseline: 1.0039x; 1.0037x over previous
.LBB0_1553:
	v_mov_b32_e32 v14, v190
	s_mul_i32 s4, s68, 0x2c0
	v_and_b32_e32 v15, 15, v14
	v_lshrrev_b32_e32 v0, 1, v14
	v_and_or_b32 v0, v0, 24, s4
	v_mul_u32_u24_e32 v1, 0x1600, v15
	v_readlane_b32 s4, v238, 6
	v_lshlrev_b32_e32 v128, 2, v1
	v_readlane_b32 s5, v238, 7
	v_cmp_gt_u32_e32 vcc, 8, v15
	v_mov_b32_e32 v4, 0
	v_lshl_add_u64 v[2:3], s[4:5], 0, v[128:129]
	v_mov_b32_e32 v128, v0
	v_lshl_add_u64 v[10:11], v[128:129], 2, v[2:3]
	s_mul_i32 s4, s10, 0x2c00
	s_mul_hi_i32 s5, s10, 0x2c00
	s_add_u32 s4, s8, s4
	s_addc_u32 s5, s9, s5
	v_lshlrev_b32_e32 v6, 1, v1
	v_mov_b32_e32 v7, v129
	v_lshl_add_u64 v[6:7], s[4:5], 0, v[6:7]
	v_lshl_add_u64 v[12:13], v[128:129], 1, v[6:7]
	v_mov_b32_e32 v20, 0
	v_mov_b32_e32 v21, 0
	v_mov_b32_e32 v22, 0
	v_mov_b32_e32 v23, 0
	v_mov_b32_e32 v24, 0
	v_mov_b32_e32 v25, 0
	v_mov_b32_e32 v26, 0
	v_mov_b32_e32 v27, 0
	v_mov_b32_e32 v28, 0
	v_mov_b32_e32 v29, 0
	v_mov_b32_e32 v30, 0
	v_mov_b32_e32 v31, 0
	v_mov_b32_e32 v32, 0
	v_mov_b32_e32 v33, 0
	v_mov_b32_e32 v34, 0
	v_mov_b32_e32 v35, 0
	v_mov_b32_e32 v36, 0
	v_mov_b32_e32 v37, 0
	v_mov_b32_e32 v38, 0
	v_mov_b32_e32 v39, 0
	v_mov_b32_e32 v40, 0
	v_mov_b32_e32 v41, 0
	v_mov_b32_e32 v42, 0
	v_mov_b32_e32 v43, 0
	v_mov_b32_e32 v44, 0
	v_mov_b32_e32 v45, 0
	v_mov_b32_e32 v46, 0
	v_mov_b32_e32 v47, 0
	v_mov_b32_e32 v48, 0
	v_mov_b32_e32 v49, 0
	v_mov_b32_e32 v50, 0
	v_mov_b32_e32 v51, 0
	v_mov_b32_e32 v52, 0
	v_mov_b32_e32 v53, 0
	v_mov_b32_e32 v54, 0
	v_mov_b32_e32 v55, 0
	v_mov_b32_e32 v56, 0
	v_mov_b32_e32 v57, 0
	v_mov_b32_e32 v58, 0
	v_mov_b32_e32 v59, 0
	v_mov_b32_e32 v60, 0
	v_mov_b32_e32 v61, 0
	v_mov_b32_e32 v62, 0
	v_mov_b32_e32 v63, 0
	v_mov_b32_e32 v64, 0
	v_mov_b32_e32 v65, 0
	v_mov_b32_e32 v66, 0
	v_mov_b32_e32 v67, 0
	v_mov_b32_e32 v68, 0
	v_mov_b32_e32 v69, 0
	v_mov_b32_e32 v70, 0
	v_mov_b32_e32 v71, 0
	v_mov_b32_e32 v72, 0
	v_mov_b32_e32 v73, 0
	v_mov_b32_e32 v74, 0
	v_mov_b32_e32 v75, 0
	v_mov_b32_e32 v76, 0
	v_mov_b32_e32 v77, 0
	v_mov_b32_e32 v78, 0
	v_mov_b32_e32 v79, 0
	v_mov_b32_e32 v80, 0
	v_mov_b32_e32 v81, 0
	v_mov_b32_e32 v82, 0
	v_mov_b32_e32 v83, 0
	s_and_saveexec_b64 s[4:5], vcc
	global_load_dwordx4 v[20:23], v[10:11], off
	global_load_dwordx4 v[24:27], v[10:11], off offset:16
	global_load_dwordx4 v[28:31], v[10:11], off offset:128
	global_load_dwordx4 v[32:35], v[10:11], off offset:144
	global_load_dwordx4 v[36:39], v[10:11], off offset:256
	global_load_dwordx4 v[40:43], v[10:11], off offset:272
	global_load_dwordx4 v[44:47], v[10:11], off offset:384
	global_load_dwordx4 v[48:51], v[10:11], off offset:400
	global_load_dwordx4 v[52:55], v[10:11], off offset:512
	global_load_dwordx4 v[56:59], v[10:11], off offset:528
	global_load_dwordx4 v[60:63], v[10:11], off offset:640
	global_load_dwordx4 v[64:67], v[10:11], off offset:656
	global_load_dwordx4 v[68:71], v[10:11], off offset:768
	global_load_dwordx4 v[72:75], v[10:11], off offset:784
	global_load_dwordx4 v[76:79], v[10:11], off offset:896
	global_load_dwordx4 v[80:83], v[10:11], off offset:912
	s_or_b64 exec, exec, s[4:5]
	global_load_dwordx4 v[84:87], v[12:13], off
	global_load_dwordx4 v[88:91], v[12:13], off offset:64
	global_load_dwordx4 v[92:95], v[12:13], off offset:128
	global_load_dwordx4 v[96:99], v[12:13], off offset:192
	global_load_dwordx4 v[100:103], v[12:13], off offset:256
	global_load_dwordx4 v[104:107], v[12:13], off offset:320
	global_load_dwordx4 v[108:111], v[12:13], off offset:384
	global_load_dwordx4 v[112:115], v[12:13], off offset:448
	s_waitcnt vmcnt(0)
	v_cvt_pk_bf16_f32 v20, v20, v21
	v_cvt_pk_bf16_f32 v21, v22, v23
	v_cvt_pk_bf16_f32 v22, v24, v25
	v_cvt_pk_bf16_f32 v23, v26, v27
	v_cvt_pk_bf16_f32 v28, v28, v29
	v_cvt_pk_bf16_f32 v29, v30, v31
	v_cvt_pk_bf16_f32 v30, v32, v33
	v_cvt_pk_bf16_f32 v31, v34, v35
	v_cvt_pk_bf16_f32 v36, v36, v37
	v_cvt_pk_bf16_f32 v37, v38, v39
	v_cvt_pk_bf16_f32 v38, v40, v41
	v_cvt_pk_bf16_f32 v39, v42, v43
	v_cvt_pk_bf16_f32 v44, v44, v45
	v_cvt_pk_bf16_f32 v45, v46, v47
	v_cvt_pk_bf16_f32 v46, v48, v49
	v_cvt_pk_bf16_f32 v47, v50, v51
	v_cvt_pk_bf16_f32 v52, v52, v53
	v_cvt_pk_bf16_f32 v53, v54, v55
	v_cvt_pk_bf16_f32 v54, v56, v57
	v_cvt_pk_bf16_f32 v55, v58, v59
	v_cvt_pk_bf16_f32 v60, v60, v61
	v_cvt_pk_bf16_f32 v61, v62, v63
	v_cvt_pk_bf16_f32 v62, v64, v65
	v_cvt_pk_bf16_f32 v63, v66, v67
	v_cvt_pk_bf16_f32 v68, v68, v69
	v_cvt_pk_bf16_f32 v69, v70, v71
	v_cvt_pk_bf16_f32 v70, v72, v73
	v_cvt_pk_bf16_f32 v71, v74, v75
	v_cvt_pk_bf16_f32 v76, v76, v77
	v_cvt_pk_bf16_f32 v77, v78, v79
	v_cvt_pk_bf16_f32 v78, v80, v81
	v_cvt_pk_bf16_f32 v79, v82, v83
	s_nop 1
	v_mfma_f32_16x16x32_bf16 v[0:3], v[20:23], v[84:87], 0
	v_mfma_f32_16x16x32_bf16 v[0:3], v[28:31], v[88:91], v[0:3]
	v_mfma_f32_16x16x32_bf16 v[0:3], v[36:39], v[92:95], v[0:3]
	v_mfma_f32_16x16x32_bf16 v[0:3], v[44:47], v[96:99], v[0:3]
	v_mfma_f32_16x16x32_bf16 v[0:3], v[52:55], v[100:103], v[0:3]
	v_mfma_f32_16x16x32_bf16 v[0:3], v[60:63], v[104:107], v[0:3]
	v_mfma_f32_16x16x32_bf16 v[0:3], v[68:71], v[108:111], v[0:3]
	v_mfma_f32_16x16x32_bf16 v[0:3], v[76:79], v[112:115], v[0:3]
	s_and_saveexec_b64 s[4:5], vcc
	global_load_dwordx4 v[20:23], v[10:11], off offset:1024
	global_load_dwordx4 v[24:27], v[10:11], off offset:1040
	global_load_dwordx4 v[28:31], v[10:11], off offset:1152
	global_load_dwordx4 v[32:35], v[10:11], off offset:1168
	global_load_dwordx4 v[36:39], v[10:11], off offset:1280
	global_load_dwordx4 v[40:43], v[10:11], off offset:1296
	global_load_dwordx4 v[44:47], v[10:11], off offset:1408
	global_load_dwordx4 v[48:51], v[10:11], off offset:1424
	global_load_dwordx4 v[52:55], v[10:11], off offset:1536
	global_load_dwordx4 v[56:59], v[10:11], off offset:1552
	global_load_dwordx4 v[60:63], v[10:11], off offset:1664
	global_load_dwordx4 v[64:67], v[10:11], off offset:1680
	global_load_dwordx4 v[68:71], v[10:11], off offset:1792
	global_load_dwordx4 v[72:75], v[10:11], off offset:1808
	global_load_dwordx4 v[76:79], v[10:11], off offset:1920
	global_load_dwordx4 v[80:83], v[10:11], off offset:1936
	s_or_b64 exec, exec, s[4:5]
	global_load_dwordx4 v[84:87], v[12:13], off offset:512
	global_load_dwordx4 v[88:91], v[12:13], off offset:576
	global_load_dwordx4 v[92:95], v[12:13], off offset:640
	global_load_dwordx4 v[96:99], v[12:13], off offset:704
	global_load_dwordx4 v[100:103], v[12:13], off offset:768
	global_load_dwordx4 v[104:107], v[12:13], off offset:832
	global_load_dwordx4 v[108:111], v[12:13], off offset:896
	global_load_dwordx4 v[112:115], v[12:13], off offset:960
	s_waitcnt vmcnt(0)
	v_cvt_pk_bf16_f32 v20, v20, v21
	v_cvt_pk_bf16_f32 v21, v22, v23
	v_cvt_pk_bf16_f32 v22, v24, v25
	v_cvt_pk_bf16_f32 v23, v26, v27
	v_cvt_pk_bf16_f32 v28, v28, v29
	v_cvt_pk_bf16_f32 v29, v30, v31
	v_cvt_pk_bf16_f32 v30, v32, v33
	v_cvt_pk_bf16_f32 v31, v34, v35
	v_cvt_pk_bf16_f32 v36, v36, v37
	v_cvt_pk_bf16_f32 v37, v38, v39
	v_cvt_pk_bf16_f32 v38, v40, v41
	v_cvt_pk_bf16_f32 v39, v42, v43
	v_cvt_pk_bf16_f32 v44, v44, v45
	v_cvt_pk_bf16_f32 v45, v46, v47
	v_cvt_pk_bf16_f32 v46, v48, v49
	v_cvt_pk_bf16_f32 v47, v50, v51
	v_cvt_pk_bf16_f32 v52, v52, v53
	v_cvt_pk_bf16_f32 v53, v54, v55
	v_cvt_pk_bf16_f32 v54, v56, v57
	v_cvt_pk_bf16_f32 v55, v58, v59
	v_cvt_pk_bf16_f32 v60, v60, v61
	v_cvt_pk_bf16_f32 v61, v62, v63
	v_cvt_pk_bf16_f32 v62, v64, v65
	v_cvt_pk_bf16_f32 v63, v66, v67
	v_cvt_pk_bf16_f32 v68, v68, v69
	v_cvt_pk_bf16_f32 v69, v70, v71
	v_cvt_pk_bf16_f32 v70, v72, v73
	v_cvt_pk_bf16_f32 v71, v74, v75
	v_cvt_pk_bf16_f32 v76, v76, v77
	v_cvt_pk_bf16_f32 v77, v78, v79
	v_cvt_pk_bf16_f32 v78, v80, v81
	v_cvt_pk_bf16_f32 v79, v82, v83
	s_nop 1
	v_mfma_f32_16x16x32_bf16 v[0:3], v[20:23], v[84:87], v[0:3]
	v_mfma_f32_16x16x32_bf16 v[0:3], v[28:31], v[88:91], v[0:3]
	v_mfma_f32_16x16x32_bf16 v[0:3], v[36:39], v[92:95], v[0:3]
	v_mfma_f32_16x16x32_bf16 v[0:3], v[44:47], v[96:99], v[0:3]
	v_mfma_f32_16x16x32_bf16 v[0:3], v[52:55], v[100:103], v[0:3]
	v_mfma_f32_16x16x32_bf16 v[0:3], v[60:63], v[104:107], v[0:3]
	v_mfma_f32_16x16x32_bf16 v[0:3], v[68:71], v[108:111], v[0:3]
	v_mfma_f32_16x16x32_bf16 v[0:3], v[76:79], v[112:115], v[0:3]
	s_and_saveexec_b64 s[4:5], vcc
	global_load_dwordx4 v[20:23], v[10:11], off offset:2048
	global_load_dwordx4 v[24:27], v[10:11], off offset:2064
	global_load_dwordx4 v[28:31], v[10:11], off offset:2176
	global_load_dwordx4 v[32:35], v[10:11], off offset:2192
	global_load_dwordx4 v[36:39], v[10:11], off offset:2304
	global_load_dwordx4 v[40:43], v[10:11], off offset:2320
	global_load_dwordx4 v[44:47], v[10:11], off offset:2432
	global_load_dwordx4 v[48:51], v[10:11], off offset:2448
	global_load_dwordx4 v[52:55], v[10:11], off offset:2560
	global_load_dwordx4 v[56:59], v[10:11], off offset:2576
	global_load_dwordx4 v[60:63], v[10:11], off offset:2688
	global_load_dwordx4 v[64:67], v[10:11], off offset:2704
	s_or_b64 exec, exec, s[4:5]
	global_load_dwordx4 v[84:87], v[12:13], off offset:1024
	global_load_dwordx4 v[88:91], v[12:13], off offset:1088
	global_load_dwordx4 v[92:95], v[12:13], off offset:1152
	global_load_dwordx4 v[96:99], v[12:13], off offset:1216
	global_load_dwordx4 v[100:103], v[12:13], off offset:1280
	global_load_dwordx4 v[104:107], v[12:13], off offset:1344
	s_waitcnt vmcnt(0)
	v_cvt_pk_bf16_f32 v20, v20, v21
	v_cvt_pk_bf16_f32 v21, v22, v23
	v_cvt_pk_bf16_f32 v22, v24, v25
	v_cvt_pk_bf16_f32 v23, v26, v27
	v_cvt_pk_bf16_f32 v28, v28, v29
	v_cvt_pk_bf16_f32 v29, v30, v31
	v_cvt_pk_bf16_f32 v30, v32, v33
	v_cvt_pk_bf16_f32 v31, v34, v35
	v_cvt_pk_bf16_f32 v36, v36, v37
	v_cvt_pk_bf16_f32 v37, v38, v39
	v_cvt_pk_bf16_f32 v38, v40, v41
	v_cvt_pk_bf16_f32 v39, v42, v43
	v_cvt_pk_bf16_f32 v44, v44, v45
	v_cvt_pk_bf16_f32 v45, v46, v47
	v_cvt_pk_bf16_f32 v46, v48, v49
	v_cvt_pk_bf16_f32 v47, v50, v51
	v_cvt_pk_bf16_f32 v52, v52, v53
	v_cvt_pk_bf16_f32 v53, v54, v55
	v_cvt_pk_bf16_f32 v54, v56, v57
	v_cvt_pk_bf16_f32 v55, v58, v59
	v_cvt_pk_bf16_f32 v60, v60, v61
	v_cvt_pk_bf16_f32 v61, v62, v63
	v_cvt_pk_bf16_f32 v62, v64, v65
	v_cvt_pk_bf16_f32 v63, v66, v67
	s_nop 1
	v_mfma_f32_16x16x32_bf16 v[0:3], v[20:23], v[84:87], v[0:3]
	v_mfma_f32_16x16x32_bf16 v[0:3], v[28:31], v[88:91], v[0:3]
	v_mfma_f32_16x16x32_bf16 v[0:3], v[36:39], v[92:95], v[0:3]
	v_mfma_f32_16x16x32_bf16 v[0:3], v[44:47], v[96:99], v[0:3]
	v_mfma_f32_16x16x32_bf16 v[0:3], v[52:55], v[100:103], v[0:3]
	v_mfma_f32_16x16x32_bf16 v[0:3], v[60:63], v[104:107], v[0:3]
	v_readlane_b32 s4, v240, 20
	v_readlane_b32 s5, v240, 21
	s_nop 2
	v_and_b32_e32 v4, 63, v14
	v_lshl_add_u32 v5, v4, 4, s33
	v_cmp_gt_u32_e32 vcc, 32, v4
	s_nop 1
	ds_write_b128 v5, v[0:3]
	s_and_b64 s[4:5], s[4:5], vcc
	v_mov_b32_e32 v2, 0
	v_mov_b32_e32 v3, 0
	v_mov_b32_e32 v0, 0
	v_mov_b32_e32 v1, 0
	s_waitcnt lgkmcnt(0)
	s_barrier
	s_and_saveexec_b64 s[6:7], s[4:5]
	s_cbranch_execz .LBB0_1599
	v_lshl_add_u32 v10, v4, 4, 0
	ds_read_b128 v[0:3], v10
	s_waitcnt lgkmcnt(0)
	v_pk_add_f32 v[4:5], v[2:3], 0 op_sel_hi:[1,0]
	v_pk_add_f32 v[6:7], v[0:1], 0 op_sel_hi:[1,0]
	ds_read_b128 v[0:3], v10 offset:1024
	s_waitcnt lgkmcnt(0)
	v_pk_add_f32 v[4:5], v[2:3], v[4:5]
	v_pk_add_f32 v[6:7], v[0:1], v[6:7]
	ds_read_b128 v[0:3], v10 offset:2048
	s_waitcnt lgkmcnt(0)
	v_pk_add_f32 v[4:5], v[2:3], v[4:5]
	v_pk_add_f32 v[6:7], v[0:1], v[6:7]
	ds_read_b128 v[0:3], v10 offset:3072
	s_waitcnt lgkmcnt(0)
	v_pk_add_f32 v[4:5], v[2:3], v[4:5]
	v_pk_add_f32 v[6:7], v[0:1], v[6:7]
	ds_read_b128 v[0:3], v10 offset:4096
	s_waitcnt lgkmcnt(0)
	v_pk_add_f32 v[4:5], v[2:3], v[4:5]
	v_pk_add_f32 v[6:7], v[0:1], v[6:7]
	ds_read_b128 v[0:3], v10 offset:5120
	s_waitcnt lgkmcnt(0)
	v_pk_add_f32 v[4:5], v[2:3], v[4:5]
	v_pk_add_f32 v[6:7], v[0:1], v[6:7]
	ds_read_b128 v[0:3], v10 offset:6144
	s_waitcnt lgkmcnt(0)
	v_pk_add_f32 v[8:9], v[2:3], v[4:5]
	ds_read_b128 v[2:5], v10 offset:7168
	v_pk_add_f32 v[6:7], v[0:1], v[6:7]
	s_waitcnt lgkmcnt(0)
	v_pk_add_f32 v[0:1], v[4:5], v[8:9]
	v_pk_add_f32 v[2:3], v[2:3], v[6:7]
